# attention: row-max / lazy-rescale check of each KV tile moved from the compute segment tail to the head of the same wave's next load segment (on top of V-read-in-compute, K ring 4 / V ring 6)
# speedup vs baseline: 1.0258x; 1.0121x over previous
; #define KROT() do { const int t_ = kprev; kprev = kcur; kcur = knext; knext = t_; } while (0)
; #define BAR() do { SBAR(); __builtin_amdgcn_s_barrier(); asm volatile("" ::: "memory"); SBAR(); } while (0)
; __device__ __forceinline__ void partialSM(f32x16& p0, f32x16& p1, float& m_reg, float& mn, float& alpha) {
;   constexpr float C = SCALE * 1.4426950408889634f;
;   float pmax = p0[0];
; #pragma unroll
;   for (int r = 1; r < 16; ++r) pmax = fmaxf(pmax, p0[r]);
; #pragma unroll
;   for (int r = 0; r < 16; ++r) pmax = fmaxf(pmax, p1[r]);
;   { auto rr = __builtin_amdgcn_permlane32_swap(__float_as_uint(pmax), __float_as_uint(pmax), false, false);
;     pmax = fmaxf(__uint_as_float(rr[0]), __uint_as_float(rr[1])); }
;   if (__builtin_expect(__all(pmax - m_reg <= THR / SCALE), 1)) { mn = m_reg; alpha = 1.f; }
;   else { mn = fmaxf(m_reg, pmax); alpha = __builtin_amdgcn_exp2f((m_reg - mn) * C); m_reg = mn; }
;   const float mnC = -mn * C;
; template <int MODE> __device__ __forceinline__ void attn_unit(const bf16_t* __restrict__ Q, const bf16_t* __restrict__ KV, const bf16_t* __restrict__ KR, bf16_t* __restrict__ O,
;                                           long rowbase, int q0, int h, LAS char* lds) {
;     ...
;   qkt3(pA0, pA1, kf, qr); partialSM(pA0, pA1, m_reg, mnA, alA); asm volatile("" : "+v"(pA0), "+v"(pA1)); KROT(); BAR();
.Lpr_wd:
	s_and_b32 s62, s68, 0x3fffffc0
	s_lshl_b32 s62, s62, 2
	s_lshr_b32 s61, s22, 4
	s_and_b32 s61, s61, 7
	s_add_i32 s62, s62, 0x18000
	s_lshl_b32 s61, s61, 8
	s_barrier
	s_waitcnt lgkmcnt(0)
	v_mfma_f32_32x32x16_bf16 v[80:95], v[16:19], v[116:119], 0
	s_mov_b32 s68, 0
	s_mov_b32 s69, s68
	v_mfma_f32_32x32x16_bf16 v[80:95], v[68:71], v[112:115], v[80:95]
	s_mov_b32 s70, s68
	s_mov_b32 s71, s68
	v_mfma_f32_32x32x16_bf16 v[32:47], v[20:23], v[116:119], 0
	s_mov_b32 s72, s68
	s_mov_b32 s73, s68
	v_mfma_f32_32x32x16_bf16 v[80:95], v[60:63], v[108:111], v[80:95]
	s_mov_b32 s74, s68
	s_mov_b32 s75, s68
	v_mfma_f32_32x32x16_bf16 v[32:47], v[64:67], v[112:115], v[32:47]
	s_mov_b32 s76, s68
	s_mov_b32 s77, s68
	v_mfma_f32_32x32x16_bf16 v[80:95], v[12:15], v[104:107], v[80:95]
	s_mov_b32 s78, s68
	s_mov_b32 s79, s68
	v_mfma_f32_32x32x16_bf16 v[32:47], v[56:59], v[108:111], v[32:47]
	s_mov_b32 s80, s68
	s_mov_b32 s81, s68
	v_mfma_f32_32x32x16_bf16 v[80:95], v[4:7], v[100:103], v[80:95]
	s_mov_b32 s82, s68
	s_mov_b32 s83, s68
	v_mfma_f32_32x32x16_bf16 v[32:47], v[8:11], v[104:107], v[32:47]
	v_mfma_f32_32x32x16_bf16 v[80:95], v[0:3], v[96:99], v[80:95]
	v_mfma_f32_32x32x16_bf16 v[32:47], v[52:55], v[100:103], v[32:47]
	v_mfma_f32_32x32x16_bf16 v[32:47], v[48:51], v[96:99], v[32:47]
	v_mov_b32_e32 v246, 0
	v_mov_b32_e32 v247, 0
	v_mov_b32_e32 v248, 0
	v_mov_b32_e32 v250, 0
	v_mov_b32_e32 v245, 0x3f80
	v_cndmask_b32_e64 v249, 0, v245, s[2:3]
	v_mov_b64_e32 v[0:1], 0
	v_mov_b64_e32 v[2:3], 0
	v_mov_b64_e32 v[4:5], 0
	v_mov_b64_e32 v[6:7], 0
	v_mov_b64_e32 v[8:9], 0
	v_mov_b64_e32 v[10:11], 0
	v_mov_b64_e32 v[12:13], 0
	v_mov_b64_e32 v[14:15], 0
	v_max3_f32 v252, v80, v81, v82
	v_max3_f32 v252, v252, v83, v84
	v_max3_f32 v252, v252, v85, v86
	v_max3_f32 v252, v252, v87, v88
	v_max3_f32 v252, v252, v89, v90
	v_max3_f32 v252, v252, v91, v92
	v_max3_f32 v252, v252, v93, v94
	v_max3_f32 v252, v252, v95, v32
	v_max3_f32 v252, v252, v33, v34
	v_max3_f32 v252, v252, v35, v36
	v_max3_f32 v252, v252, v37, v38
	v_max3_f32 v252, v252, v39, v40
	v_max3_f32 v252, v252, v41, v42
	v_max3_f32 v252, v252, v43, v44
	v_max3_f32 v252, v252, v45, v46
	v_max_f32_e32 v252, v252, v47
	v_mov_b32_e32 v253, v252
	s_nop 1
	v_permlane32_swap_b32_e32 v252, v253
	v_max_f32_e32 v252, v252, v253
	v_and_b32_e32 v253, 0xffff0000, v252
	v_xor_b32_e32 v255, 0x80000000, v253
	v_lshrrev_b32_e32 v251, 16, v255
	v_sub_f32_e32 v64, v32, v253
	v_sub_f32_e32 v65, v33, v253
	v_sub_f32_e32 v66, v34, v253
	v_sub_f32_e32 v67, v35, v253
	v_sub_f32_e32 v68, v36, v253
	v_sub_f32_e32 v69, v37, v253
	v_sub_f32_e32 v70, v38, v253
	v_sub_f32_e32 v71, v39, v253
	v_sub_f32_e32 v72, v40, v253
	v_sub_f32_e32 v73, v41, v253
	v_sub_f32_e32 v74, v42, v253
	v_sub_f32_e32 v75, v43, v253
	v_sub_f32_e32 v76, v44, v253
	v_sub_f32_e32 v77, v45, v253
	v_sub_f32_e32 v78, v46, v253
	v_sub_f32_e32 v79, v47, v253
	v_sub_f32_e32 v80, v80, v253
	v_sub_f32_e32 v81, v81, v253
	v_exp_f32_e32 v32, v80
	v_sub_f32_e32 v82, v82, v253
	v_exp_f32_e32 v33, v81
	v_sub_f32_e32 v83, v83, v253
	v_exp_f32_e32 v34, v82
	v_sub_f32_e32 v84, v84, v253
	v_exp_f32_e32 v35, v83
	v_sub_f32_e32 v85, v85, v253
	v_exp_f32_e32 v36, v84
	v_sub_f32_e32 v86, v86, v253
	v_exp_f32_e32 v37, v85
	v_sub_f32_e32 v87, v87, v253
	v_exp_f32_e32 v38, v86
	v_sub_f32_e32 v88, v88, v253
	v_exp_f32_e32 v39, v87
	v_sub_f32_e32 v89, v89, v253
	v_exp_f32_e32 v40, v88
	v_sub_f32_e32 v90, v90, v253
	v_exp_f32_e32 v41, v89
	v_sub_f32_e32 v91, v91, v253
	v_exp_f32_e32 v42, v90
	v_sub_f32_e32 v92, v92, v253
	v_exp_f32_e32 v43, v91
	v_sub_f32_e32 v93, v93, v253
	v_exp_f32_e32 v44, v92
	v_sub_f32_e32 v94, v94, v253
	v_exp_f32_e32 v45, v93
	v_sub_f32_e32 v95, v95, v253
	v_exp_f32_e32 v46, v94
	v_exp_f32_e32 v47, v95
	s_nop 0
	s_barrier
	s_lshl_b64 s[70:71], s[58:59], 18
	s_and_b32 s63, s84, 48
	s_or_b32 s70, s70, s63
	s_lshl_b64 s[58:59], s[58:59], 23
	v_lshl_add_u64 v[220:221], s[70:71], 0, v[200:201]
	s_add_u32 s70, s6, s61
	s_addc_u32 s71, 0, 0
	s_and_b32 s6, s84, 0x3ffffff0
	s_add_u32 s6, s6, s61
	v_or_b32_e32 v16, s58, v202
	v_add_u32_e32 v18, s60, v193
	s_addc_u32 s60, 0, 0
	v_mov_b32_e32 v17, s59
	v_lshl_or_b32 v16, v18, 11, v16
	s_add_u32 s58, s6, s58
	v_lshl_add_u64 v[222:223], s[70:71], 0, v[16:17]
	s_addc_u32 s59, s60, s59
	v_mov_b64_e32 v[30:31], v[14:15]
	v_lshl_add_u32 v211, v192, 2, s62
	v_lshl_add_u64 v[224:225], s[58:59], 0, v[204:205]
	v_mov_b32_e32 v213, 0
	s_mov_b32 s6, 1
	s_movk_i32 s70, 0x6000
	s_movk_i32 s69, 0x3000
	s_mov_b32 s63, 0x8000
	v_mov_b64_e32 v[28:29], v[12:13]
	v_mov_b64_e32 v[26:27], v[10:11]
	v_mov_b64_e32 v[24:25], v[8:9]
	v_mov_b64_e32 v[22:23], v[6:7]
	v_mov_b64_e32 v[20:21], v[4:5]
	v_mov_b64_e32 v[18:19], v[2:3]
	v_mov_b64_e32 v[16:17], v[0:1]
	s_mov_b32 s98, 0
	s_mov_b32 s99, 0x3000
	s_mov_b32 s100, 0x8000
	s_mov_b32 s101, 0
.LBB0_570:
	v_max3_f32 v252, v80, v81, v82
	v_max3_f32 v252, v252, v83, v84
	v_max3_f32 v252, v252, v85, v86
	v_max3_f32 v252, v252, v87, v88
	v_max3_f32 v252, v252, v89, v90
	v_max3_f32 v252, v252, v91, v92
	v_max3_f32 v252, v252, v93, v94
	v_max3_f32 v252, v252, v95, v64
	v_max3_f32 v252, v252, v65, v66
	v_max3_f32 v252, v252, v67, v68
	v_max3_f32 v252, v252, v69, v70
	v_max3_f32 v252, v252, v71, v72
	v_max3_f32 v252, v252, v73, v74
	v_max3_f32 v252, v252, v75, v76
	v_max3_f32 v252, v252, v77, v78
	v_max_f32_e32 v252, v252, v79
	v_cmp_nge_f32_e32 vcc, s23, v252
	s_nop 3
	s_cmp_lg_u64 vcc, 0
	s_cbranch_scc1 .Lrare_b

; __device__ __forceinline__ void partialSM(f32x16& p0, f32x16& p1, float& m_reg, float& mn, float& alpha) {
;   constexpr float C = SCALE * 1.4426950408889634f;
;   float pmax = p0[0];
; #pragma unroll
;   for (int r = 1; r < 16; ++r) pmax = fmaxf(pmax, p0[r]);
; #pragma unroll
;   for (int r = 0; r < 16; ++r) pmax = fmaxf(pmax, p1[r]);
;   { auto rr = __builtin_amdgcn_permlane32_swap(__float_as_uint(pmax), __float_as_uint(pmax), false, false);
;     pmax = fmaxf(__uint_as_float(rr[0]), __uint_as_float(rr[1])); }
;   if (__builtin_expect(__all(pmax - m_reg <= THR / SCALE), 1)) { mn = m_reg; alpha = 1.f; }
;   else { mn = fmaxf(m_reg, pmax); alpha = __builtin_amdgcn_exp2f((m_reg - mn) * C); m_reg = mn; }
.Lwd_a:
	s_barrier
	s_waitcnt lgkmcnt(0)
	v_mfma_f32_32x32x16_bf16 v[80:95], v[246:249], v[248:251], 0
	v_exp_f32_e32 v64, v64
	v_add_f32_e32 v213, v32, v213
	ds_read_b64_tr_b16 v[148:149], v217 offset:0
	v_exp_f32_e32 v65, v65
	v_add_f32_e32 v213, v33, v213
	ds_read_b64_tr_b16 v[150:151], v217 offset:512
	v_mfma_f32_32x32x16_bf16 v[80:95], v[48:51], v[116:119], v[80:95]
	v_exp_f32_e32 v66, v66
	v_add_f32_e32 v213, v34, v213
	ds_read_b64_tr_b16 v[140:141], v217 offset:1024
	v_exp_f32_e32 v67, v67
	v_add_f32_e32 v213, v35, v213
	ds_read_b64_tr_b16 v[142:143], v217 offset:1536
	v_mfma_f32_32x32x16_bf16 v[48:63], v[52:55], v[116:119], 0
	v_exp_f32_e32 v68, v68
	v_add_f32_e32 v213, v36, v213
	ds_read_b64_tr_b16 v[132:133], v217 offset:2048
	v_exp_f32_e32 v69, v69
	v_add_f32_e32 v213, v37, v213
	ds_read_b64_tr_b16 v[134:135], v217 offset:2560
	v_mfma_f32_32x32x16_bf16 v[48:63], v[246:249], v[248:251], v[48:63]
	v_exp_f32_e32 v70, v70
	v_add_f32_e32 v213, v38, v213
	ds_read_b64_tr_b16 v[124:125], v217 offset:3072
	v_exp_f32_e32 v71, v71
	v_add_f32_e32 v213, v39, v213
	ds_read_b64_tr_b16 v[126:127], v217 offset:3584
	v_mfma_f32_32x32x16_bf16 v[80:95], v[188:191], v[112:115], v[80:95]
	v_exp_f32_e32 v72, v72
	v_add_f32_e32 v213, v40, v213
	ds_read_b64_tr_b16 v[144:145], v217 offset:4096
	v_exp_f32_e32 v73, v73
	v_add_f32_e32 v213, v41, v213
	ds_read_b64_tr_b16 v[146:147], v217 offset:4608
	v_mfma_f32_32x32x16_bf16 v[48:63], v[184:187], v[112:115], v[48:63]
	v_exp_f32_e32 v74, v74
	v_add_f32_e32 v213, v42, v213
	ds_read_b64_tr_b16 v[136:137], v217 offset:5120
	v_exp_f32_e32 v75, v75
	v_add_f32_e32 v213, v43, v213
	ds_read_b64_tr_b16 v[138:139], v217 offset:5632
	v_mfma_f32_32x32x16_bf16 v[80:95], v[180:183], v[108:111], v[80:95]
	v_exp_f32_e32 v76, v76
	v_add_f32_e32 v213, v44, v213
	ds_read_b64_tr_b16 v[128:129], v217 offset:6144
	v_exp_f32_e32 v77, v77
	v_add_f32_e32 v213, v45, v213
	ds_read_b64_tr_b16 v[130:131], v217 offset:6656
	v_mfma_f32_32x32x16_bf16 v[48:63], v[176:179], v[108:111], v[48:63]
	v_exp_f32_e32 v78, v78
	v_add_f32_e32 v213, v46, v213
	ds_read_b64_tr_b16 v[120:121], v217 offset:7168
	v_exp_f32_e32 v79, v79
	v_add_f32_e32 v213, v47, v213
	ds_read_b64_tr_b16 v[122:123], v217 offset:7680
	v_mfma_f32_32x32x16_bf16 v[80:95], v[172:175], v[104:107], v[80:95]
	v_add_f32_e32 v245, v64, v65
	v_add_f32_e32 v245, v66, v245
	v_add_f32_e32 v245, v67, v245
	v_add_f32_e32 v245, v68, v245
	v_add_f32_e32 v245, v69, v245
	v_add_f32_e32 v245, v70, v245
	v_mfma_f32_32x32x16_bf16 v[48:63], v[168:171], v[104:107], v[48:63]
	v_add_f32_e32 v245, v71, v245
	v_add_f32_e32 v245, v72, v245
	v_add_f32_e32 v245, v73, v245
	v_add_f32_e32 v245, v74, v245
	v_add_f32_e32 v245, v75, v245
	v_mfma_f32_32x32x16_bf16 v[80:95], v[164:167], v[100:103], v[80:95]
	v_add_f32_e32 v245, v76, v245
	v_add_f32_e32 v245, v77, v245
	v_add_f32_e32 v245, v78, v245
	v_add_f32_e32 v245, v79, v245
	v_add_f32_e32 v213, v245, v213
	v_mfma_f32_32x32x16_bf16 v[48:63], v[160:163], v[100:103], v[48:63]
	v_cvt_pk_bf16_f32 v32, v32, v33
	v_cvt_pk_bf16_f32 v33, v34, v35
	v_cvt_pk_bf16_f32 v34, v36, v37
	v_cvt_pk_bf16_f32 v35, v38, v39
	v_cvt_pk_bf16_f32 v36, v40, v41
	v_cvt_pk_bf16_f32 v37, v42, v43
	v_mfma_f32_32x32x16_bf16 v[80:95], v[156:159], v[96:99], v[80:95]
	v_cvt_pk_bf16_f32 v38, v44, v45
	v_cvt_pk_bf16_f32 v39, v46, v47
	v_cvt_pk_bf16_f32 v64, v64, v65
	v_cvt_pk_bf16_f32 v65, v66, v67
	v_cvt_pk_bf16_f32 v66, v68, v69
	v_cvt_pk_bf16_f32 v67, v70, v71
	v_mfma_f32_32x32x16_bf16 v[48:63], v[152:155], v[96:99], v[48:63]
	v_cvt_pk_bf16_f32 v68, v72, v73
	v_cvt_pk_bf16_f32 v69, v74, v75
	v_cvt_pk_bf16_f32 v70, v76, v77
	v_cvt_pk_bf16_f32 v71, v78, v79
	s_waitcnt lgkmcnt(0)
	v_mfma_f32_32x32x16_bf16 v[0:15], v[32:35], v[148:151], v[0:15]
	v_exp_f32_e32 v40, v88
	v_exp_f32_e32 v41, v89
	v_mfma_f32_32x32x16_bf16 v[16:31], v[32:35], v[144:147], v[16:31]
	v_exp_f32_e32 v42, v90
	v_exp_f32_e32 v43, v91
	v_mfma_f32_32x32x16_bf16 v[0:15], v[36:39], v[140:143], v[0:15]
	v_exp_f32_e32 v44, v92
	v_exp_f32_e32 v45, v93
	v_mfma_f32_32x32x16_bf16 v[16:31], v[36:39], v[136:139], v[16:31]
	v_exp_f32_e32 v46, v94
	v_exp_f32_e32 v47, v95
	v_mfma_f32_32x32x16_bf16 v[0:15], v[64:67], v[132:135], v[0:15]
	v_exp_f32_e32 v32, v80
	v_exp_f32_e32 v33, v81
	v_mfma_f32_32x32x16_bf16 v[16:31], v[64:67], v[128:131], v[16:31]
	v_exp_f32_e32 v34, v82
	v_exp_f32_e32 v35, v83
	v_mfma_f32_32x32x16_bf16 v[0:15], v[68:71], v[124:127], v[0:15]
	v_exp_f32_e32 v36, v84
	v_exp_f32_e32 v37, v85
	v_mfma_f32_32x32x16_bf16 v[16:31], v[68:71], v[120:123], v[16:31]
	v_exp_f32_e32 v38, v86
	v_exp_f32_e32 v39, v87
	s_barrier
	v_max3_f32 v252, v80, v81, v82
	v_max3_f32 v252, v252, v83, v84
	v_max3_f32 v252, v252, v85, v86
	v_max3_f32 v252, v252, v87, v88
	v_max3_f32 v252, v252, v89, v90
	v_max3_f32 v252, v252, v91, v92
	v_max3_f32 v252, v252, v93, v94
	v_max3_f32 v252, v252, v95, v48
	v_max3_f32 v252, v252, v49, v50
	v_max3_f32 v252, v252, v51, v52
	v_max3_f32 v252, v252, v53, v54
	v_max3_f32 v252, v252, v55, v56
	v_max3_f32 v252, v252, v57, v58
	v_max3_f32 v252, v252, v59, v60
	v_max3_f32 v252, v252, v61, v62
	v_max_f32_e32 v252, v252, v63
	v_cmp_nge_f32_e32 vcc, s23, v252
	s_nop 3
	s_cmp_lg_u64 vcc, 0
	s_cbranch_scc1 .Lrare_a
.Ljoin_a:
	s_cmp_gt_u32 s6, 60
	s_cselect_b64 s[58:59], -1, 0
	s_cmp_gt_u32 s6, 60
	s_cbranch_scc1 .Lni_b
	v_lshl_add_u64 v[64:65], v[226:227], 0, s[18:19]
	s_add_i32 m0, s65, s98
	s_nop 0
	global_load_lds_dwordx4 v[64:65], off
	s_and_b64 vcc, exec, s[4:5]
	s_cbranch_vccnz .Lnr_b
	v_lshl_add_u64 v[64:65], s[28:29], 0, v[220:221]
	v_lshl_add_u64 v[64:65], v[64:65], 0, s[24:25]
	s_add_i32 s60, s65, s98
	s_add_i32 m0, s60, 0x2000
	s_nop 0
	global_load_lds_dwordx4 v[64:65], off

; template <int MODE> __device__ __forceinline__ void attn_unit(const bf16_t* __restrict__ Q, const bf16_t* __restrict__ KV, const bf16_t* __restrict__ KR, bf16_t* __restrict__ O,
;                                           long rowbase, int q0, int h, LAS char* lds) {
;     ...
;   for (int j = 1; j + 1 < NT; j += 2) {
;     STEP(j, pB0, pB1, mnB, alB, pA0, pA1, alA);
;     STEP(j + 1, pA0, pA1, mnA, alA, pB0, pB1, alB);
;   }
.Lwd_b:
	s_barrier
	s_waitcnt lgkmcnt(0)
	v_mfma_f32_32x32x16_bf16 v[80:95], v[246:249], v[248:251], 0
	v_exp_f32_e32 v48, v48
	v_add_f32_e32 v213, v32, v213
	ds_read_b64_tr_b16 v[148:149], v217 offset:0
	v_exp_f32_e32 v49, v49
	v_add_f32_e32 v213, v33, v213
	ds_read_b64_tr_b16 v[150:151], v217 offset:512
	v_mfma_f32_32x32x16_bf16 v[80:95], v[64:67], v[116:119], v[80:95]
	v_exp_f32_e32 v50, v50
	v_add_f32_e32 v213, v34, v213
	ds_read_b64_tr_b16 v[140:141], v217 offset:1024
	v_exp_f32_e32 v51, v51
	v_add_f32_e32 v213, v35, v213
	ds_read_b64_tr_b16 v[142:143], v217 offset:1536
	v_mfma_f32_32x32x16_bf16 v[64:79], v[68:71], v[116:119], 0
	v_exp_f32_e32 v52, v52
	v_add_f32_e32 v213, v36, v213
	ds_read_b64_tr_b16 v[132:133], v217 offset:2048
	v_exp_f32_e32 v53, v53
	v_add_f32_e32 v213, v37, v213
	ds_read_b64_tr_b16 v[134:135], v217 offset:2560
	v_mfma_f32_32x32x16_bf16 v[64:79], v[246:249], v[248:251], v[64:79]
	v_exp_f32_e32 v54, v54
	v_add_f32_e32 v213, v38, v213
	ds_read_b64_tr_b16 v[124:125], v217 offset:3072
	v_exp_f32_e32 v55, v55
	v_add_f32_e32 v213, v39, v213
	ds_read_b64_tr_b16 v[126:127], v217 offset:3584
	v_mfma_f32_32x32x16_bf16 v[80:95], v[188:191], v[112:115], v[80:95]
	v_exp_f32_e32 v56, v56
	v_add_f32_e32 v213, v40, v213
	ds_read_b64_tr_b16 v[144:145], v217 offset:4096
	v_exp_f32_e32 v57, v57
	v_add_f32_e32 v213, v41, v213
	ds_read_b64_tr_b16 v[146:147], v217 offset:4608
	v_mfma_f32_32x32x16_bf16 v[64:79], v[184:187], v[112:115], v[64:79]
	v_exp_f32_e32 v58, v58
	v_add_f32_e32 v213, v42, v213
	ds_read_b64_tr_b16 v[136:137], v217 offset:5120
	v_exp_f32_e32 v59, v59
	v_add_f32_e32 v213, v43, v213
	ds_read_b64_tr_b16 v[138:139], v217 offset:5632
	v_mfma_f32_32x32x16_bf16 v[80:95], v[180:183], v[108:111], v[80:95]
	v_exp_f32_e32 v60, v60
	v_add_f32_e32 v213, v44, v213
	ds_read_b64_tr_b16 v[128:129], v217 offset:6144
	v_exp_f32_e32 v61, v61
	v_add_f32_e32 v213, v45, v213
	ds_read_b64_tr_b16 v[130:131], v217 offset:6656
	v_mfma_f32_32x32x16_bf16 v[64:79], v[176:179], v[108:111], v[64:79]
	v_exp_f32_e32 v62, v62
	v_add_f32_e32 v213, v46, v213
	ds_read_b64_tr_b16 v[120:121], v217 offset:7168
	v_exp_f32_e32 v63, v63
	v_add_f32_e32 v213, v47, v213
	ds_read_b64_tr_b16 v[122:123], v217 offset:7680
	v_mfma_f32_32x32x16_bf16 v[80:95], v[172:175], v[104:107], v[80:95]
	v_add_f32_e32 v245, v48, v49
	v_add_f32_e32 v245, v50, v245
	v_add_f32_e32 v245, v51, v245
	v_add_f32_e32 v245, v52, v245
	v_add_f32_e32 v245, v53, v245
	v_add_f32_e32 v245, v54, v245
	v_mfma_f32_32x32x16_bf16 v[64:79], v[168:171], v[104:107], v[64:79]
	v_add_f32_e32 v245, v55, v245
	v_add_f32_e32 v245, v56, v245
	v_add_f32_e32 v245, v57, v245
	v_add_f32_e32 v245, v58, v245
	v_add_f32_e32 v245, v59, v245
	v_mfma_f32_32x32x16_bf16 v[80:95], v[164:167], v[100:103], v[80:95]
	v_add_f32_e32 v245, v60, v245
	v_add_f32_e32 v245, v61, v245
	v_add_f32_e32 v245, v62, v245
	v_add_f32_e32 v245, v63, v245
	v_add_f32_e32 v213, v245, v213
	v_mfma_f32_32x32x16_bf16 v[64:79], v[160:163], v[100:103], v[64:79]
	v_cvt_pk_bf16_f32 v32, v32, v33
	v_cvt_pk_bf16_f32 v33, v34, v35
	v_cvt_pk_bf16_f32 v34, v36, v37
	v_cvt_pk_bf16_f32 v35, v38, v39
	v_cvt_pk_bf16_f32 v36, v40, v41
	v_cvt_pk_bf16_f32 v37, v42, v43
	v_mfma_f32_32x32x16_bf16 v[80:95], v[156:159], v[96:99], v[80:95]
	v_cvt_pk_bf16_f32 v38, v44, v45
	v_cvt_pk_bf16_f32 v39, v46, v47
	v_cvt_pk_bf16_f32 v48, v48, v49
	v_cvt_pk_bf16_f32 v49, v50, v51
	v_cvt_pk_bf16_f32 v50, v52, v53
	v_cvt_pk_bf16_f32 v51, v54, v55
	v_mfma_f32_32x32x16_bf16 v[64:79], v[152:155], v[96:99], v[64:79]
	v_cvt_pk_bf16_f32 v52, v56, v57
	v_cvt_pk_bf16_f32 v53, v58, v59
	v_cvt_pk_bf16_f32 v54, v60, v61
	v_cvt_pk_bf16_f32 v55, v62, v63
	s_waitcnt lgkmcnt(0)
	v_mfma_f32_32x32x16_bf16 v[0:15], v[32:35], v[148:151], v[0:15]
	v_exp_f32_e32 v40, v88
	v_exp_f32_e32 v41, v89
	v_mfma_f32_32x32x16_bf16 v[16:31], v[32:35], v[144:147], v[16:31]
	v_exp_f32_e32 v42, v90
	v_exp_f32_e32 v43, v91
	v_mfma_f32_32x32x16_bf16 v[0:15], v[36:39], v[140:143], v[0:15]
	v_exp_f32_e32 v44, v92
	v_exp_f32_e32 v45, v93
	v_mfma_f32_32x32x16_bf16 v[16:31], v[36:39], v[136:139], v[16:31]
	v_exp_f32_e32 v46, v94
	v_exp_f32_e32 v47, v95
	v_mfma_f32_32x32x16_bf16 v[0:15], v[48:51], v[132:135], v[0:15]
	v_exp_f32_e32 v32, v80
	v_exp_f32_e32 v33, v81
	v_mfma_f32_32x32x16_bf16 v[16:31], v[48:51], v[128:131], v[16:31]
	v_exp_f32_e32 v34, v82
	v_exp_f32_e32 v35, v83
	v_mfma_f32_32x32x16_bf16 v[0:15], v[52:55], v[124:127], v[0:15]
	v_exp_f32_e32 v36, v84
	v_exp_f32_e32 v37, v85
	v_mfma_f32_32x32x16_bf16 v[16:31], v[52:55], v[120:123], v[16:31]
	v_exp_f32_e32 v38, v86
	v_exp_f32_e32 v39, v87
	s_add_i32 s6, s6, 2
	s_barrier
	s_addk_i32 s63, 0x4000
	v_lshl_add_u64 v[220:221], v[220:221], 0, s[12:13]
	v_lshl_add_u64 v[222:223], v[222:223], 0, s[10:11]
	v_lshl_add_u64 v[224:225], v[224:225], 0, s[10:11]
	s_and_b64 vcc, exec, s[58:59]
	s_cbranch_vccnz .LBB0_597
	s_mov_b32 s68, s70
	s_mov_b32 s70, s71
	s_branch .LBB0_570

; #define SBAR() __builtin_amdgcn_sched_barrier(0)
; #define BAR() do { SBAR(); __builtin_amdgcn_s_barrier(); asm volatile("" ::: "memory"); SBAR(); } while (0)
; __device__ __forceinline__ void partialSM(f32x16& p0, f32x16& p1, float& m_reg, float& mn, float& alpha) {
;   constexpr float C = SCALE * 1.4426950408889634f;
;   float pmax = p0[0];
; #pragma unroll
;   for (int r = 1; r < 16; ++r) pmax = fmaxf(pmax, p0[r]);
; #pragma unroll
;   for (int r = 0; r < 16; ++r) pmax = fmaxf(pmax, p1[r]);
;   { auto rr = __builtin_amdgcn_permlane32_swap(__float_as_uint(pmax), __float_as_uint(pmax), false, false);
;     pmax = fmaxf(__uint_as_float(rr[0]), __uint_as_float(rr[1])); }
;   if (__builtin_expect(__all(pmax - m_reg <= THR / SCALE), 1)) { mn = m_reg; alpha = 1.f; }
;   else { mn = fmaxf(m_reg, pmax); alpha = __builtin_amdgcn_exp2f((m_reg - mn) * C); m_reg = mn; }
; template <int MODE> __device__ __forceinline__ void attn_unit(const bf16_t* __restrict__ Q, const bf16_t* __restrict__ KV, const bf16_t* __restrict__ KR, bf16_t* __restrict__ O,
;                                           long rowbase, int q0, int h, LAS char* lds) {
;     ...
;   STEP(NT - 1, pB0, pB1, mnB, alB, pA0, pA1, alA);
;   if (wid < 4) BAR();
;   finishSM2(pB0, pB1, alB, l_reg, pa0, pa1, pa2, pa3); SBAR();
;   vload16(vf, vbase + ((NT - 1) & 3) * VSLOT); asm volatile("s_waitcnt lgkmcnt(0)" ::: "memory"); SBAR();
;   pv3(o, vf, pa0, pa1, pa2, pa3);
.Ljoin_u:
	ds_read_b128 v[48:51], v231 offset:36864
	ds_read_b128 v[52:55], v231 offset:37376
	ds_read_b128 v[188:191], v231 offset:38912
	ds_read_b128 v[184:187], v231 offset:39424
	ds_read_b128 v[180:183], v231 offset:40960
	ds_read_b128 v[176:179], v231 offset:41472
	ds_read_b128 v[172:175], v231 offset:43008
	ds_read_b128 v[168:171], v231 offset:43520
	ds_read_b128 v[164:167], v231 offset:45056
	ds_read_b128 v[160:163], v231 offset:45568
	ds_read_b128 v[156:159], v231 offset:47104
	ds_read_b128 v[152:155], v231 offset:47616
	s_waitcnt vmcnt(0) lgkmcnt(0)
	s_barrier
	s_waitcnt lgkmcnt(0)
	v_mfma_f32_32x32x16_bf16 v[80:95], v[246:249], v[248:251], 0
	v_exp_f32_e32 v64, v64
	v_add_f32_e32 v213, v32, v213
	ds_read_b64_tr_b16 v[148:149], v233 offset:0
	v_exp_f32_e32 v65, v65
	v_add_f32_e32 v213, v33, v213
	ds_read_b64_tr_b16 v[150:151], v233 offset:512
	v_mfma_f32_32x32x16_bf16 v[80:95], v[48:51], v[116:119], v[80:95]
	v_exp_f32_e32 v66, v66
	v_add_f32_e32 v213, v34, v213
	ds_read_b64_tr_b16 v[140:141], v233 offset:1024
	v_exp_f32_e32 v67, v67
	v_add_f32_e32 v213, v35, v213
	ds_read_b64_tr_b16 v[142:143], v233 offset:1536
	v_mfma_f32_32x32x16_bf16 v[48:63], v[52:55], v[116:119], 0
	v_exp_f32_e32 v68, v68
	v_add_f32_e32 v213, v36, v213
	ds_read_b64_tr_b16 v[132:133], v233 offset:2048
	v_exp_f32_e32 v69, v69
	v_add_f32_e32 v213, v37, v213
	ds_read_b64_tr_b16 v[134:135], v233 offset:2560
	v_mfma_f32_32x32x16_bf16 v[48:63], v[246:249], v[248:251], v[48:63]
	v_exp_f32_e32 v70, v70
	v_add_f32_e32 v213, v38, v213
	ds_read_b64_tr_b16 v[124:125], v233 offset:3072
	v_exp_f32_e32 v71, v71
	v_add_f32_e32 v213, v39, v213
	ds_read_b64_tr_b16 v[126:127], v233 offset:3584
	v_mfma_f32_32x32x16_bf16 v[80:95], v[188:191], v[112:115], v[80:95]
	v_exp_f32_e32 v72, v72
	v_add_f32_e32 v213, v40, v213
	ds_read_b64_tr_b16 v[144:145], v233 offset:4096
	v_exp_f32_e32 v73, v73
	v_add_f32_e32 v213, v41, v213
	ds_read_b64_tr_b16 v[146:147], v233 offset:4608
	v_mfma_f32_32x32x16_bf16 v[48:63], v[184:187], v[112:115], v[48:63]
	v_exp_f32_e32 v74, v74
	v_add_f32_e32 v213, v42, v213
	ds_read_b64_tr_b16 v[136:137], v233 offset:5120
	v_exp_f32_e32 v75, v75
	v_add_f32_e32 v213, v43, v213
	ds_read_b64_tr_b16 v[138:139], v233 offset:5632
	v_mfma_f32_32x32x16_bf16 v[80:95], v[180:183], v[108:111], v[80:95]
	v_exp_f32_e32 v76, v76
	v_add_f32_e32 v213, v44, v213
	ds_read_b64_tr_b16 v[128:129], v233 offset:6144
	v_exp_f32_e32 v77, v77
	v_add_f32_e32 v213, v45, v213
	ds_read_b64_tr_b16 v[130:131], v233 offset:6656
	v_mfma_f32_32x32x16_bf16 v[48:63], v[176:179], v[108:111], v[48:63]
	v_exp_f32_e32 v78, v78
	v_add_f32_e32 v213, v46, v213
	ds_read_b64_tr_b16 v[120:121], v233 offset:7168
	v_exp_f32_e32 v79, v79
	v_add_f32_e32 v213, v47, v213
	ds_read_b64_tr_b16 v[122:123], v233 offset:7680
	v_mfma_f32_32x32x16_bf16 v[80:95], v[172:175], v[104:107], v[80:95]
	v_add_f32_e32 v245, v64, v65
	v_add_f32_e32 v245, v66, v245
	v_add_f32_e32 v245, v67, v245
	v_add_f32_e32 v245, v68, v245
	v_add_f32_e32 v245, v69, v245
	v_add_f32_e32 v245, v70, v245
	v_mfma_f32_32x32x16_bf16 v[48:63], v[168:171], v[104:107], v[48:63]
	v_add_f32_e32 v245, v71, v245
	v_add_f32_e32 v245, v72, v245
	v_add_f32_e32 v245, v73, v245
	v_add_f32_e32 v245, v74, v245
	v_add_f32_e32 v245, v75, v245
	v_mfma_f32_32x32x16_bf16 v[80:95], v[164:167], v[100:103], v[80:95]
	v_add_f32_e32 v245, v76, v245
	v_add_f32_e32 v245, v77, v245
	v_add_f32_e32 v245, v78, v245
	v_add_f32_e32 v245, v79, v245
	v_add_f32_e32 v213, v245, v213
	v_mfma_f32_32x32x16_bf16 v[48:63], v[160:163], v[100:103], v[48:63]
	v_cvt_pk_bf16_f32 v32, v32, v33
	v_cvt_pk_bf16_f32 v33, v34, v35
	v_cvt_pk_bf16_f32 v34, v36, v37
	v_cvt_pk_bf16_f32 v35, v38, v39
	v_cvt_pk_bf16_f32 v36, v40, v41
	v_cvt_pk_bf16_f32 v37, v42, v43
	v_mfma_f32_32x32x16_bf16 v[80:95], v[156:159], v[96:99], v[80:95]
	v_cvt_pk_bf16_f32 v38, v44, v45
	v_cvt_pk_bf16_f32 v39, v46, v47
	v_cvt_pk_bf16_f32 v64, v64, v65
	v_cvt_pk_bf16_f32 v65, v66, v67
	v_cvt_pk_bf16_f32 v66, v68, v69
	v_cvt_pk_bf16_f32 v67, v70, v71
	v_mfma_f32_32x32x16_bf16 v[48:63], v[152:155], v[96:99], v[48:63]
	v_cvt_pk_bf16_f32 v68, v72, v73
	v_cvt_pk_bf16_f32 v69, v74, v75
	v_cvt_pk_bf16_f32 v70, v76, v77
	v_cvt_pk_bf16_f32 v71, v78, v79
	s_waitcnt lgkmcnt(0)
	v_mfma_f32_32x32x16_bf16 v[0:15], v[32:35], v[148:151], v[0:15]
	v_exp_f32_e32 v40, v88
	v_exp_f32_e32 v41, v89
	v_mfma_f32_32x32x16_bf16 v[16:31], v[32:35], v[144:147], v[16:31]
	v_exp_f32_e32 v42, v90
	v_exp_f32_e32 v43, v91
	v_mfma_f32_32x32x16_bf16 v[0:15], v[36:39], v[140:143], v[0:15]
	v_exp_f32_e32 v44, v92
	v_exp_f32_e32 v45, v93
	v_mfma_f32_32x32x16_bf16 v[16:31], v[36:39], v[136:139], v[16:31]
	v_exp_f32_e32 v46, v94
	v_exp_f32_e32 v47, v95
	v_mfma_f32_32x32x16_bf16 v[0:15], v[64:67], v[132:135], v[0:15]
	v_exp_f32_e32 v32, v80
	v_exp_f32_e32 v33, v81
	v_mfma_f32_32x32x16_bf16 v[16:31], v[64:67], v[128:131], v[16:31]
	v_exp_f32_e32 v34, v82
	v_exp_f32_e32 v35, v83
	v_mfma_f32_32x32x16_bf16 v[0:15], v[68:71], v[124:127], v[0:15]
	v_exp_f32_e32 v36, v84
	v_exp_f32_e32 v37, v85
	v_mfma_f32_32x32x16_bf16 v[16:31], v[68:71], v[120:123], v[16:31]
	v_exp_f32_e32 v38, v86
	v_exp_f32_e32 v39, v87
	s_barrier
	s_and_b64 vcc, exec, s[4:5]
	s_cbranch_vccnz .LBB0_603
	s_barrier
.LBB0_603:
	v_max3_f32 v252, v80, v81, v82
	v_max3_f32 v252, v252, v83, v84
	v_max3_f32 v252, v252, v85, v86
	v_max3_f32 v252, v252, v87, v88
	v_max3_f32 v252, v252, v89, v90
	v_max3_f32 v252, v252, v91, v92
	v_max3_f32 v252, v252, v93, v94
	v_max3_f32 v252, v252, v95, v48
	v_max3_f32 v252, v252, v49, v50
	v_max3_f32 v252, v252, v51, v52
	v_max3_f32 v252, v252, v53, v54
	v_max3_f32 v252, v252, v55, v56
	v_max3_f32 v252, v252, v57, v58
	v_max3_f32 v252, v252, v59, v60
	v_max3_f32 v252, v252, v61, v62
	v_max_f32_e32 v252, v252, v63
	v_cmp_nge_f32_e32 vcc, s23, v252
	s_nop 3
	s_cmp_lg_u64 vcc, 0
	s_cbranch_scc1 .Lrare_t

; __device__ __forceinline__ void partialSM(f32x16& p0, f32x16& p1, float& m_reg, float& mn, float& alpha) {
;     ...
;   if (__builtin_expect(__all(pmax - m_reg <= THR / SCALE), 1)) { mn = m_reg; alpha = 1.f; }
;   else { mn = fmaxf(m_reg, pmax); alpha = __builtin_amdgcn_exp2f((m_reg - mn) * C); m_reg = mn; }
.Lrare_t:
	v_mov_b32_e32 v253, v252
	s_nop 1
	v_permlane32_swap_b32_e32 v252, v253
	v_max_f32_e32 v252, v252, v253
	v_max_f32_e32 v252, 0, v252
	v_lshlrev_b32_e32 v253, 16, v251
	v_sub_f32_e32 v255, v252, v253
	v_and_b32_e32 v255, 0xffff0000, v255
	v_add_f32_e32 v152, v255, v253
	v_xor_b32_e32 v255, 0x80000000, v255
	v_lshrrev_b32_e32 v251, 16, v255
	v_sub_f32_e32 v153, 0, v152
	v_exp_f32_e32 v153, v153
	v_sub_f32_e32 v48, v48, v152
	v_sub_f32_e32 v49, v49, v152
	v_sub_f32_e32 v50, v50, v152
	v_sub_f32_e32 v51, v51, v152
	v_sub_f32_e32 v52, v52, v152
	v_sub_f32_e32 v53, v53, v152
	v_sub_f32_e32 v54, v54, v152
	v_sub_f32_e32 v55, v55, v152
	v_sub_f32_e32 v56, v56, v152
	v_sub_f32_e32 v57, v57, v152
	v_sub_f32_e32 v58, v58, v152
	v_sub_f32_e32 v59, v59, v152
	v_sub_f32_e32 v60, v60, v152
	v_sub_f32_e32 v61, v61, v152
	v_sub_f32_e32 v62, v62, v152
	v_sub_f32_e32 v63, v63, v152
	v_mul_f32_e32 v213, v213, v153
	v_sub_f32_e32 v154, v80, v152
	v_sub_f32_e32 v253, v81, v152
	v_exp_f32_e32 v32, v154
	v_sub_f32_e32 v154, v82, v152
	v_exp_f32_e32 v33, v253
	v_sub_f32_e32 v253, v83, v152
	v_exp_f32_e32 v34, v154
	v_sub_f32_e32 v154, v84, v152
	v_exp_f32_e32 v35, v253
	v_sub_f32_e32 v253, v85, v152
	v_exp_f32_e32 v36, v154
	v_sub_f32_e32 v154, v86, v152
	v_exp_f32_e32 v37, v253
	v_sub_f32_e32 v253, v87, v152
	v_exp_f32_e32 v38, v154
	v_sub_f32_e32 v154, v88, v152
	v_exp_f32_e32 v39, v253
	v_sub_f32_e32 v253, v89, v152
	v_exp_f32_e32 v40, v154
	v_sub_f32_e32 v154, v90, v152
	v_exp_f32_e32 v41, v253
	v_sub_f32_e32 v253, v91, v152
	v_exp_f32_e32 v42, v154
	v_sub_f32_e32 v154, v92, v152
	v_exp_f32_e32 v43, v253
	v_sub_f32_e32 v253, v93, v152
	v_exp_f32_e32 v44, v154
	v_sub_f32_e32 v154, v94, v152
	v_exp_f32_e32 v45, v253
	v_sub_f32_e32 v253, v95, v152
	v_exp_f32_e32 v46, v154
	v_exp_f32_e32 v47, v253
	s_nop 0
	s_and_saveexec_b64 s[56:57], s[2:3]
	ds_write_b32 v211, v153 offset:128
	s_or_b64 exec, exec, s[56:57]
	s_waitcnt lgkmcnt(0)
	v_add_u32_e32 v245, s62, v232
	ds_read_b128 v[80:83], v245 offset:224
	ds_read_b128 v[84:87], v245 offset:192
	ds_read_b128 v[88:91], v245 offset:160
	ds_read_b128 v[92:95], v245 offset:128
	s_waitcnt lgkmcnt(0)
	v_pk_mul_f32 v[12:13], v[12:13], v[80:81]
	v_pk_mul_f32 v[8:9], v[8:9], v[84:85]
	v_pk_mul_f32 v[4:5], v[4:5], v[88:89]
	v_pk_mul_f32 v[14:15], v[14:15], v[82:83]
	v_pk_mul_f32 v[10:11], v[10:11], v[86:87]
	v_pk_mul_f32 v[6:7], v[6:7], v[90:91]
	v_pk_mul_f32 v[2:3], v[2:3], v[94:95]
	v_pk_mul_f32 v[0:1], v[0:1], v[92:93]
	v_pk_mul_f32 v[28:29], v[28:29], v[80:81]
	v_pk_mul_f32 v[24:25], v[24:25], v[84:85]
	v_pk_mul_f32 v[20:21], v[20:21], v[88:89]
	v_pk_mul_f32 v[30:31], v[30:31], v[82:83]
	v_pk_mul_f32 v[26:27], v[26:27], v[86:87]
	v_pk_mul_f32 v[22:23], v[22:23], v[90:91]
	v_pk_mul_f32 v[18:19], v[18:19], v[94:95]
	v_pk_mul_f32 v[16:17], v[16:17], v[92:93]
	s_branch .Ljoin_t
.Lrare_u:
	v_mov_b32_e32 v253, v252
	s_nop 1
	v_permlane32_swap_b32_e32 v252, v253
	v_max_f32_e32 v252, v252, v253
	v_max_f32_e32 v252, 0, v252
	v_lshlrev_b32_e32 v253, 16, v251
	v_sub_f32_e32 v255, v252, v253
	v_and_b32_e32 v255, 0xffff0000, v255
	v_add_f32_e32 v152, v255, v253
	v_xor_b32_e32 v255, 0x80000000, v255
	v_lshrrev_b32_e32 v251, 16, v255
	v_sub_f32_e32 v153, 0, v152
	v_exp_f32_e32 v153, v153
	v_sub_f32_e32 v64, v64, v152
	v_sub_f32_e32 v65, v65, v152
	v_sub_f32_e32 v66, v66, v152
	v_sub_f32_e32 v67, v67, v152
	v_sub_f32_e32 v68, v68, v152
	v_sub_f32_e32 v69, v69, v152
	v_sub_f32_e32 v70, v70, v152
	v_sub_f32_e32 v71, v71, v152
	v_sub_f32_e32 v72, v72, v152
	v_sub_f32_e32 v73, v73, v152
	v_sub_f32_e32 v74, v74, v152
	v_sub_f32_e32 v75, v75, v152
	v_sub_f32_e32 v76, v76, v152
	v_sub_f32_e32 v77, v77, v152
	v_sub_f32_e32 v78, v78, v152
	v_sub_f32_e32 v79, v79, v152
	v_mul_f32_e32 v213, v213, v153
	v_sub_f32_e32 v154, v80, v152
	v_sub_f32_e32 v253, v81, v152
	v_exp_f32_e32 v32, v154
	v_sub_f32_e32 v154, v82, v152
	v_exp_f32_e32 v33, v253
	v_sub_f32_e32 v253, v83, v152
	v_exp_f32_e32 v34, v154
	v_sub_f32_e32 v154, v84, v152
	v_exp_f32_e32 v35, v253
	v_sub_f32_e32 v253, v85, v152
	v_exp_f32_e32 v36, v154
	v_sub_f32_e32 v154, v86, v152
	v_exp_f32_e32 v37, v253
	v_sub_f32_e32 v253, v87, v152
	v_exp_f32_e32 v38, v154
	v_sub_f32_e32 v154, v88, v152
	v_exp_f32_e32 v39, v253
	v_sub_f32_e32 v253, v89, v152
	v_exp_f32_e32 v40, v154
	v_sub_f32_e32 v154, v90, v152
	v_exp_f32_e32 v41, v253
	v_sub_f32_e32 v253, v91, v152
	v_exp_f32_e32 v42, v154
	v_sub_f32_e32 v154, v92, v152
	v_exp_f32_e32 v43, v253
	v_sub_f32_e32 v253, v93, v152
	v_exp_f32_e32 v44, v154
	v_sub_f32_e32 v154, v94, v152
	v_exp_f32_e32 v45, v253
	v_sub_f32_e32 v253, v95, v152
	v_exp_f32_e32 v46, v154
	v_exp_f32_e32 v47, v253
	s_nop 0
	s_and_saveexec_b64 s[60:61], s[2:3]
	ds_write_b32 v211, v153 offset:128
	s_or_b64 exec, exec, s[60:61]
	s_waitcnt lgkmcnt(0)
	v_add_u32_e32 v245, s62, v232
	ds_read_b128 v[80:83], v245 offset:224
	ds_read_b128 v[84:87], v245 offset:192
	ds_read_b128 v[88:91], v245 offset:160
	ds_read_b128 v[92:95], v245 offset:128
	s_waitcnt lgkmcnt(0)
	v_pk_mul_f32 v[12:13], v[12:13], v[80:81]
	v_pk_mul_f32 v[8:9], v[8:9], v[84:85]
	v_pk_mul_f32 v[4:5], v[4:5], v[88:89]
	v_pk_mul_f32 v[14:15], v[14:15], v[82:83]
	v_pk_mul_f32 v[10:11], v[10:11], v[86:87]
	v_pk_mul_f32 v[6:7], v[6:7], v[90:91]
	v_pk_mul_f32 v[2:3], v[2:3], v[94:95]
	v_pk_mul_f32 v[0:1], v[0:1], v[92:93]
	v_pk_mul_f32 v[28:29], v[28:29], v[80:81]
	v_pk_mul_f32 v[24:25], v[24:25], v[84:85]
	v_pk_mul_f32 v[20:21], v[20:21], v[88:89]
	v_pk_mul_f32 v[30:31], v[30:31], v[82:83]
	v_pk_mul_f32 v[26:27], v[26:27], v[86:87]
	v_pk_mul_f32 v[22:23], v[22:23], v[90:91]
	v_pk_mul_f32 v[18:19], v[18:19], v[94:95]
	v_pk_mul_f32 v[16:17], v[16:17], v[92:93]
	s_branch .Ljoin_u
.LBB0_605:
	v_readlane_b32 s82, v254, 16
	v_readlane_b32 s83, v254, 17
